# grid barrier release path flattened: last XCD leader bumps all eight per-XCD generation flags; other leaders wait on their own flag (TOPGEN hop removed)
# speedup vs baseline: 1.0004x; 1.0004x over previous
; DI int TID() { int t = threadIdx.x; asm volatile("" : "+v"(t)); return t; }
; DI void grid_barrier_light(unsigned* ctr, unsigned target) {
;   asm volatile("s_waitcnt vmcnt(0)" ::: "memory");
;   __syncthreads();
;   if (TID() == 0) {
;     __builtin_amdgcn_fence(__ATOMIC_RELEASE, "agent");
;     asm volatile("s_waitcnt vmcnt(0)" ::: "memory");
;     __hip_atomic_fetch_add(ctr, 1u, __ATOMIC_RELAXED, __HIP_MEMORY_SCOPE_AGENT);
;     while (__hip_atomic_load(ctr, __ATOMIC_RELAXED, __HIP_MEMORY_SCOPE_AGENT) < target) { }
;     __builtin_amdgcn_fence(__ATOMIC_ACQUIRE, "agent");
;     asm volatile("s_waitcnt vmcnt(0)" ::: "memory");
;   }
;   __syncthreads();
; }
.Lxb_ready:
	s_waitcnt lgkmcnt(0)
	s_and_b32 s9, s100, 0xff
	s_lshl_b32 s9, s9, 8
	v_mov_b32_e32 v1, s9
	v_mov_b32_e32 v2, 1
	global_atomic_add v3, v1, v2, s[6:7] sc0
	s_bfe_u32 s14, s100, 0x100008
	s_mul_i32 s14, s14, s8
	s_add_u32 s9, s9, 0x800
	v_mov_b32_e32 v4, s9
	s_waitcnt vmcnt(0)
	v_readfirstlane_b32 s15, v3
	s_nop 3
	s_add_u32 s15, s15, 1
	s_cmp_eq_u32 s15, s14
	s_cbranch_scc0 .Lxb_follower
	buffer_wbl2 sc1
	s_waitcnt vmcnt(0)
	v_mov_b32_e32 v1, 0x1000
	global_atomic_add v3, v1, v2, s[6:7] sc0
	s_lshr_b32 s14, s100, 24
	s_mul_i32 s14, s14, s8
	v_mov_b32_e32 v1, 0x1100
	s_waitcnt vmcnt(0)
	v_readfirstlane_b32 s15, v3
	s_nop 3
	s_add_u32 s15, s15, 1
	s_cmp_eq_u32 s15, s14
	s_cbranch_scc0 .Lxb_follower
	v_mov_b32_e32 v1, 0x800
	global_atomic_add v1, v2, s[6:7]
	v_mov_b32_e32 v1, 0x900
	global_atomic_add v1, v2, s[6:7]
	v_mov_b32_e32 v1, 0xa00
	global_atomic_add v1, v2, s[6:7]
	v_mov_b32_e32 v1, 0xb00
	global_atomic_add v1, v2, s[6:7]
	v_mov_b32_e32 v1, 0xc00
	global_atomic_add v1, v2, s[6:7]
	v_mov_b32_e32 v1, 0xd00
	global_atomic_add v1, v2, s[6:7]
	v_mov_b32_e32 v1, 0xe00
	global_atomic_add v1, v2, s[6:7]
	v_mov_b32_e32 v1, 0xf00
	global_atomic_add v1, v2, s[6:7]
	buffer_inv sc1
	s_waitcnt vmcnt(0)
	s_branch .LBB0_2025
